# tile order of ffn_in and a_in: 4 row panels x 8 column tiles per XCD round (was 2 x 16), fewer L2 misses per K-step
# speedup vs baseline: 1.0386x; 1.0381x over previous
.LBB0_66:
	s_or_b64 exec, exec, s[4:5]
	s_mov_b64 s[4:5], s[0:1]
	v_mov_b32_e32 v8, v157
	s_cmpk_lt_i32 s2, 0xb00
	s_cselect_b64 s[24:25], -1, 0
	s_cmpk_gt_i32 s2, 0xaff
	v_readfirstlane_b32 s20, v8
	s_cbranch_scc1 .LBB0_84
	v_lshlrev_b32_e32 v0, 4, v8
	v_add_u32_e32 v1, 0x2000, v0
	v_ashrrev_i32_e32 v2, 31, v1
	v_lshrrev_b32_e32 v2, 22, v2
	v_add_u32_e32 v2, v1, v2
	v_ashrrev_i32_e32 v9, 10, v2
	v_mul_i32_i24_e32 v2, 0x400, v9
	v_sub_u32_e32 v1, v1, v2
	v_lshrrev_b32_e32 v2, 4, v1
	v_bitop3_b32 v1, v2, v1, 32 bitop3:0x6c
	v_ashrrev_i32_e32 v2, 31, v1
	v_lshrrev_b32_e32 v2, 26, v2
	v_add_u32_e32 v2, v1, v2
	v_lshlrev_b32_e32 v3, 3, v9
	v_ashrrev_i32_e32 v10, 6, v2
	v_and_b32_e32 v3, -16, v3
	v_add_u32_e32 v3, v10, v3
	v_and_b32_e32 v4, 3, v10
	s_mov_b32 s8, 0x1fffe0
	v_lshrrev_b32_e32 v5, 2, v3
	v_lshlrev_b32_e32 v6, 1, v3
	v_and_b32_e32 v2, 0xc0, v2
	v_and_or_b32 v4, v3, s8, v4
	v_and_b32_e32 v5, 4, v5
	v_and_b32_e32 v6, 24, v6
	v_sub_u32_e32 v1, v1, v2
	v_mov_b32_e32 v2, 1
	v_or3_b32 v4, v4, v5, v6
	v_lshlrev_b32_e32 v5, 5, v9
	v_ashrrev_i16_sdwa v1, v2, sext(v1) dst_sel:DWORD dst_unused:UNUSED_PAD src0_sel:DWORD src1_sel:BYTE_0
	v_and_b32_e32 v5, 32, v5
	v_bfe_i32 v11, v1, 0, 16
	v_add_lshl_u32 v1, v5, v11, 1
	v_lshl_add_u32 v128, v4, 11, v1
	v_lshrrev_b32_e32 v250, 3, v157
	v_and_b32_e32 v251, 6, v250
	v_and_b32_e32 v252, 7, v157
	v_xor_b32_e32 v251, v251, v252
	v_lshlrev_b32_e32 v251, 4, v251
	v_and_b32_e32 v252, 12, v250
	v_lshlrev_b32_e32 v252, 1, v252
	v_and_b32_e32 v253, 16, v250
	v_lshrrev_b32_e32 v253, 2, v253
	v_or_b32_e32 v252, v252, v253
	v_and_b32_e32 v253, 35, v250
	v_or_b32_e32 v250, v252, v253
	v_mul_u32_u24_e32 v250, 0x800, v250
	v_add_u32_e32 v128, v250, v251
	v_add_u32_e32 v128, 0x20000, v128
	v_lshl_add_u32 v130, v3, 11, v1
	v_lshrrev_b32_e32 v250, 3, v157
	v_and_b32_e32 v251, 6, v250
	v_and_b32_e32 v252, 7, v157
	v_xor_b32_e32 v251, v251, v252
	v_lshlrev_b32_e32 v251, 4, v251
	v_mul_u32_u24_e32 v250, 0x800, v250
	v_add_u32_e32 v130, v250, v251
	v_add_u32_e32 v130, 0x20000, v130
	v_bfe_i32 v1, v8, 27, 1
	v_lshrrev_b32_e32 v1, 22, v1
	v_add_u32_e32 v1, v0, v1
	s_load_dwordx2 s[4:5], s[4:5], 0x80
	v_and_b32_e32 v1, 0xfffffc00, v1
	v_sub_u32_e32 v0, v0, v1
	v_lshrrev_b32_e32 v1, 4, v0
	v_ashrrev_i32_e32 v3, 31, v8
	v_bitop3_b32 v0, v1, v0, 32 bitop3:0x6c
	v_lshrrev_b32_e32 v3, 26, v3
	v_ashrrev_i32_e32 v1, 31, v0
	v_add_u32_e32 v3, v8, v3
	s_waitcnt lgkmcnt(0)
	s_add_u32 s3, s4, 0x6000000
	v_lshrrev_b32_e32 v1, 26, v1
	v_ashrrev_i32_e32 v13, 6, v3
	s_addc_u32 s35, s5, 0
	v_add_u32_e32 v1, v0, v1
	v_lshlrev_b32_e32 v3, 3, v13
	s_add_u32 s50, s4, 0x400000
	v_ashrrev_i32_e32 v12, 6, v1
	v_and_b32_e32 v3, -16, v3
	s_addc_u32 s51, s5, 0
	v_add_u32_e32 v3, v12, v3
	v_and_b32_e32 v4, 3, v12
	s_ashr_i32 s53, s2, 31
	v_and_or_b32 v4, v3, s8, v4
	s_lshr_b32 s8, s53, 29
	s_add_i32 s8, s2, s8
	s_ashr_i32 s17, s20, 6
	s_ashr_i32 s9, s8, 3
	s_and_b32 s8, s8, -8
	s_ashr_i32 s21, s20, 8
	s_lshl_b32 s52, s17, 10
	s_sub_i32 s8, s2, s8
	s_cmp_lt_i32 s8, 0
	s_movk_i32 s54, 0x161
	s_cselect_b32 s10, s54, 0x160
	s_mul_i32 s8, s10, s8
	s_add_i32 s8, s8, s9
	s_mul_hi_i32 s9, s8, 0x2e8ba2e9
	s_lshr_b32 s10, s9, 31
	s_ashr_i32 s9, s9, 3
	s_add_i32 s9, s9, s10
	s_lshl_b32 s10, s9, 1
	s_mul_i32 s9, s9, 44
	s_sub_i32 s8, s8, s9
	s_bfe_u32 s9, s8, 0x10007
	s_add_i32 s9, s8, s9
	s_bfe_i32 s11, s9, 0x80000
	s_and_b32 s9, s9, 0xfe
	s_sub_i32 s8, s8, s9
	s_sext_i32_i16 s11, s11
	s_sext_i32_i8 s8, s8
	v_lshrrev_b32_e32 v5, 2, v3
	v_lshlrev_b32_e32 v6, 1, v3
	v_and_b32_e32 v1, 0xc0, v1
	s_lshr_b32 s16, s11, 1
	s_add_i32 s44, s10, s8
	s_cmp_eq_u32 s42, 0x100
	s_cbranch_scc0 .Lwgm_p_0
	s_lshr_b32 s99, s2, 3
	s_and_b32 s44, s99, 3
	s_lshr_b32 s16, s99, 2
	s_and_b32 s98, s2, 7
	s_lshl_b32 s98, s98, 4
	s_add_i32 s44, s44, s98
.Lwgm_p_0:
	v_and_b32_e32 v5, 4, v5
	v_and_b32_e32 v6, 24, v6
	v_sub_u32_e32 v0, v0, v1
	s_ashr_i32 s45, s44, 31
	s_bfe_i64 s[10:11], s[16:17], 0x100000
	v_or3_b32 v4, v4, v5, v6
	v_lshlrev_b32_e32 v5, 5, v13
	v_ashrrev_i16_sdwa v0, v2, sext(v0) dst_sel:DWORD dst_unused:UNUSED_PAD src0_sel:DWORD src1_sel:BYTE_0
	s_lshl_b64 s[8:9], s[44:45], 19
	s_lshl_b64 s[10:11], s[10:11], 19
	v_and_b32_e32 v5, 32, v5
	v_bfe_i32 v14, v0, 0, 16
	s_add_u32 s46, s50, s10
	v_add_lshl_u32 v0, v5, v14, 1
	s_addc_u32 s47, s51, s11
	s_add_i32 s55, s52, 0
	v_lshl_add_u32 v132, v4, 11, v0
	v_lshrrev_b32_e32 v250, 3, v157
	v_and_b32_e32 v251, 6, v250
	v_and_b32_e32 v252, 7, v157
	v_xor_b32_e32 v251, v251, v252
	v_lshlrev_b32_e32 v251, 4, v251
	v_and_b32_e32 v252, 12, v250
	v_lshlrev_b32_e32 v252, 1, v252
	v_and_b32_e32 v253, 16, v250
	v_lshrrev_b32_e32 v253, 2, v253
	v_or_b32_e32 v252, v252, v253
	v_and_b32_e32 v253, 35, v250
	v_or_b32_e32 v250, v252, v253
	v_mul_u32_u24_e32 v250, 0x800, v250
	v_add_u32_e32 v132, v250, v251
	s_add_i32 m0, s55, 0x10000
	v_lshl_add_u32 v134, v3, 11, v0
	v_lshrrev_b32_e32 v250, 3, v157
	v_and_b32_e32 v251, 6, v250
	v_and_b32_e32 v252, 7, v157
	v_xor_b32_e32 v251, v251, v252
	v_lshlrev_b32_e32 v251, 4, v251
	v_mul_u32_u24_e32 v250, 0x800, v250
	v_add_u32_e32 v134, v250, v251
	global_load_lds_dwordx4 v132, s[46:47]
	s_add_i32 m0, s55, 0x12000
	s_add_u32 s10, s46, 0x40000
	global_load_lds_dwordx4 v128, s[46:47]
	s_addc_u32 s11, s47, 0
	s_add_i32 m0, s55, 0x14000
	v_mov_b32_e32 v133, 0
	global_load_lds_dwordx4 v132, s[10:11]
	s_add_i32 m0, s55, 0x16000
	s_add_u32 s48, s3, s8
	s_addc_u32 s49, s35, s9
	s_add_i32 s56, s55, 0x2000
	global_load_lds_dwordx4 v128, s[10:11]
	s_mov_b32 m0, s55
	s_add_u32 s8, s48, 0x40000
	global_load_lds_dwordx4 v134, s[48:49]
	s_mov_b32 m0, s56
	s_addc_u32 s9, s49, 0
	s_add_i32 s57, s55, 0x4000
	global_load_lds_dwordx4 v130, s[48:49]
	s_mov_b32 m0, s57
	s_add_i32 s58, s55, 0x6000
	global_load_lds_dwordx4 v134, s[8:9]
	s_mov_b32 m0, s58
	v_mov_b32_e32 v129, v133
	global_load_lds_dwordx4 v130, s[8:9]
	v_mov_b32_e32 v135, v133
	v_mov_b32_e32 v131, v133
	s_cmp_eq_u32 s21, 1
	s_mov_b32 s59, 0
	v_lshl_add_u64 v[6:7], s[46:47], 0, v[132:133]
	v_lshl_add_u64 v[4:5], s[46:47], 0, v[128:129]
	v_lshl_add_u64 v[0:1], s[48:49], 0, v[134:135]
	s_cselect_b64 s[8:9], -1, 0
	s_cmp_lg_u32 s21, 1
	v_lshl_add_u64 v[2:3], s[48:49], 0, v[130:131]
	s_cbranch_scc1 .LBB0_69
	s_barrier

.LBB0_72:
	s_add_i32 s59, s59, 1
	s_mul_i32 s4, s59, s62
	s_mul_hi_u32 s5, s59, s63
	s_add_i32 s5, s5, s4
	s_mul_i32 s4, s59, s63
	s_add_u32 s28, s4, s2
	s_addc_u32 s29, s5, s53
	v_cmp_gt_i64_e32 vcc, s[28:29], v[142:143]
	v_cmp_lt_i64_e64 s[4:5], s[28:29], v[140:141]
	s_cbranch_vccnz .LBB0_74
	s_cmp_eq_u32 s42, 0x100
	s_cbranch_scc0 .Lwgm_orig_0
	s_and_b32 s98, s2, 7
	s_lshr_b32 s99, s2, 3
	s_cmp_lt_u32 s59, 8
	s_cbranch_scc0 .Lwgm_tail_0
	s_lshr_b32 s100, s59, 1
	s_lshl_b32 s100, s100, 2
	s_and_b32 s101, s99, 3
	s_add_i32 s26, s100, s101
	s_and_b32 s100, s59, 1
	s_lshl_b32 s100, s100, 3
	s_lshr_b32 s101, s99, 2
	s_add_i32 s22, s100, s101
	s_branch .Lwgm_join_0
.Lwgm_tail_0:
	s_sub_i32 s100, s59, 8
	s_lshl_b32 s100, s100, 5
	s_add_i32 s100, s100, s99
	s_mul_hi_u32 s26, s100, 0x2aaaaaab
	s_mul_i32 s101, s26, 6
	s_sub_i32 s101, s100, s101
	s_add_i32 s22, s101, 16
.Lwgm_join_0:
	s_lshl_b32 s98, s98, 4
	s_add_i32 s26, s26, s98
	s_branch .LBB0_74
.Lwgm_orig_0:
	s_ashr_i32 s22, s28, 31
	s_lshr_b32 s22, s22, 29
	s_add_i32 s22, s28, s22
	s_ashr_i32 s23, s22, 3
	s_and_b32 s22, s22, -8
	s_sub_i32 s22, s28, s22
	s_cmp_lt_i32 s22, 0
	s_cselect_b32 s26, s54, 0x160
	s_mul_i32 s22, s26, s22
	s_add_i32 s22, s22, s23
	s_mul_hi_i32 s23, s22, 0x2e8ba2e9
	s_lshr_b32 s26, s23, 31
	s_ashr_i32 s23, s23, 3
	s_add_i32 s23, s23, s26
	s_lshl_b32 s26, s23, 1
	s_sub_i32 s27, 0x80, s26
	s_min_i32 s27, s27, 2
	s_abs_i32 s28, s27
	v_cvt_f32_u32_e32 v0, s28
	s_sub_i32 s30, 0, s28
	s_mul_i32 s23, s23, 44
	s_sub_i32 s23, s22, s23
	v_rcp_iflag_f32_e32 v0, v0
	s_abs_i32 s22, s23
	s_xor_b32 s29, s23, s27
	s_ashr_i32 s29, s29, 31
	v_mul_f32_e32 v0, 0x4f7ffffe, v0
	v_cvt_u32_f32_e32 v0, v0
	s_nop 0
	v_readfirstlane_b32 s31, v0
	s_mul_i32 s30, s30, s31
	s_mul_hi_u32 s30, s31, s30
	s_add_i32 s31, s31, s30
	s_mul_hi_u32 s30, s22, s31
	s_mul_i32 s31, s30, s28
	s_sub_i32 s22, s22, s31
	s_add_i32 s45, s30, 1
	s_sub_i32 s31, s22, s28
	s_cmp_ge_u32 s22, s28
	s_cselect_b32 s30, s45, s30
	s_cselect_b32 s22, s31, s22
	s_add_i32 s31, s30, 1
	s_cmp_ge_u32 s22, s28
	s_cselect_b32 s22, s31, s30
	s_xor_b32 s22, s22, s29
	s_sub_i32 s22, s22, s29
	s_mul_i32 s27, s22, s27
	s_sub_i32 s23, s23, s27
	s_add_i32 s26, s23, s26

.LBB0_241:
	s_ashr_i32 s10, s12, 3
	s_add_i32 s10, s14, s10
	s_ashr_i32 s11, s10, 31
	s_lshr_b32 s11, s11, 27
	s_add_i32 s11, s10, s11
	s_ashr_i32 s12, s11, 5
	s_andn2_b32 s11, s11, 31
	s_sub_i32 s10, s10, s11
	s_bfe_u32 s11, s10, 0x10007
	s_add_i32 s11, s10, s11
	s_bfe_i32 s13, s11, 0x80000
	s_and_b32 s11, s11, 0xfe
	s_sub_i32 s10, s10, s11
	s_lshl_b32 s12, s12, 1
	s_sext_i32_i16 s13, s13
	s_sext_i32_i8 s10, s10
	s_add_i32 s14, s12, s10
	s_ashr_i32 s20, s13, 1
	s_cmp_eq_u32 s42, 0x100
	s_cbranch_scc0 .Lwgm_p_1
	s_lshr_b32 s99, s2, 3
	s_and_b32 s14, s99, 3
	s_lshr_b32 s20, s99, 2
	s_and_b32 s98, s2, 7
	s_lshl_b32 s98, s98, 4
	s_add_i32 s14, s14, s98
.Lwgm_p_1:
.LBB0_242:
	s_andn2_b64 vcc, exec, s[8:9]
	s_cbranch_vccnz .LBB0_298
	v_ashrrev_i32_e32 v1, 31, v8
	v_lshrrev_b32_e32 v1, 26, v1
	v_add_u32_e32 v1, v8, v1
	v_ashrrev_i32_e32 v9, 6, v1
	v_bfe_i32 v1, v8, 27, 1
	v_lshlrev_b32_e32 v0, 4, v8
	v_lshrrev_b32_e32 v1, 22, v1
	v_add_u32_e32 v1, v0, v1
	v_and_b32_e32 v1, 0xfffffc00, v1
	v_sub_u32_e32 v1, v0, v1
	v_lshrrev_b32_e32 v2, 4, v1
	v_bitop3_b32 v1, v2, v1, 32 bitop3:0x6c
	v_ashrrev_i32_e32 v3, 31, v1
	v_lshrrev_b32_e32 v3, 26, v3
	v_add_u32_e32 v3, v1, v3
	v_lshlrev_b32_e32 v2, 3, v9
	v_ashrrev_i32_e32 v10, 6, v3
	v_and_b32_e32 v3, 0xc0, v3
	v_and_b32_e32 v2, -16, v2
	v_sub_u32_e32 v1, v1, v3
	v_mov_b32_e32 v3, 1
	v_add_u32_e32 v2, v10, v2
	v_ashrrev_i16_sdwa v1, v3, sext(v1) dst_sel:DWORD dst_unused:UNUSED_PAD src0_sel:DWORD src1_sel:BYTE_0
	v_lshlrev_b32_e32 v4, 5, v9
	v_bfe_i32 v11, v1, 0, 16
	v_lshlrev_b32_e32 v1, 1, v2
	v_lshrrev_b32_e32 v5, 2, v2
	v_and_b32_e32 v6, 3, v10
	s_mov_b32 s9, 0x1fffe0
	v_and_b32_e32 v4, 32, v4
	v_and_b32_e32 v1, 24, v1
	v_and_b32_e32 v5, 4, v5
	v_and_or_b32 v6, v2, s9, v6
	v_or3_b32 v1, v6, v5, v1
	v_add_lshl_u32 v4, v4, v11, 1
	v_add_u32_e32 v0, 0x2000, v0
	v_lshl_add_u32 v162, v1, 11, v4
	v_lshrrev_b32_e32 v250, 3, v157
	v_and_b32_e32 v251, 6, v250
	v_and_b32_e32 v252, 7, v157
	v_xor_b32_e32 v251, v251, v252
	v_lshlrev_b32_e32 v251, 4, v251
	v_and_b32_e32 v252, 12, v250
	v_lshlrev_b32_e32 v252, 1, v252
	v_and_b32_e32 v253, 16, v250
	v_lshrrev_b32_e32 v253, 2, v253
	v_or_b32_e32 v252, v252, v253
	v_and_b32_e32 v253, 35, v250
	v_or_b32_e32 v250, v252, v253
	v_mul_u32_u24_e32 v250, 0x800, v250
	v_add_u32_e32 v162, v250, v251
	v_ashrrev_i32_e32 v1, 31, v0
	v_lshrrev_b32_e32 v1, 22, v1
	v_add_u32_e32 v1, v0, v1
	v_ashrrev_i32_e32 v12, 10, v1
	v_mul_i32_i24_e32 v1, 0x400, v12
	v_sub_u32_e32 v0, v0, v1
	v_lshrrev_b32_e32 v1, 4, v0
	v_bitop3_b32 v0, v1, v0, 32 bitop3:0x6c
	v_lshl_add_u32 v160, v2, 11, v4
	v_lshrrev_b32_e32 v250, 3, v157
	v_and_b32_e32 v251, 6, v250
	v_and_b32_e32 v252, 7, v157
	v_xor_b32_e32 v251, v251, v252
	v_lshlrev_b32_e32 v251, 4, v251
	v_mul_u32_u24_e32 v250, 0x800, v250
	v_add_u32_e32 v160, v250, v251
	v_ashrrev_i32_e32 v2, 31, v0
	v_lshrrev_b32_e32 v2, 26, v2
	s_waitcnt lgkmcnt(0)
	s_add_u32 s35, s16, 0x6000000
	v_add_u32_e32 v2, v0, v2
	s_addc_u32 s47, s17, 0
	v_lshlrev_b32_e32 v1, 3, v12
	v_ashrrev_i32_e32 v13, 6, v2
	v_and_b32_e32 v2, 0xc0, v2
	s_add_u32 s49, s16, 0x4600000
	v_and_b32_e32 v1, -16, v1
	v_sub_u32_e32 v0, v0, v2
	s_addc_u32 s70, s17, 0
	s_ashr_i32 s8, s3, 6
	v_add_u32_e32 v1, v13, v1
	v_ashrrev_i16_sdwa v0, v3, sext(v0) dst_sel:DWORD dst_unused:UNUSED_PAD src0_sel:DWORD src1_sel:BYTE_0
	v_and_b32_e32 v3, 3, v13
	s_ashr_i32 s15, s14, 31
	s_ashr_i32 s21, s20, 31
	v_and_or_b32 v3, v1, s9, v3
	s_ashr_i32 s9, s3, 8
	s_lshl_b32 s71, s8, 10
	s_lshl_b64 s[10:11], s[14:15], 19
	s_lshl_b64 s[12:13], s[20:21], 19
	s_add_u32 s66, s49, s12
	v_lshlrev_b32_e32 v4, 5, v12
	v_bfe_i32 v14, v0, 0, 16
	v_lshlrev_b32_e32 v0, 1, v1
	v_lshrrev_b32_e32 v2, 2, v1
	s_addc_u32 s67, s70, s13
	s_add_i32 s74, s71, 0
	v_and_b32_e32 v4, 32, v4
	v_and_b32_e32 v0, 24, v0
	v_and_b32_e32 v2, 4, v2
	s_add_i32 m0, s74, 0x10000
	v_or3_b32 v0, v3, v2, v0
	v_add_lshl_u32 v2, v4, v14, 1
	global_load_lds_dwordx4 v162, s[66:67]
	s_add_i32 m0, s74, 0x12000
	v_lshl_add_u32 v166, v0, 11, v2
	v_lshrrev_b32_e32 v250, 3, v157
	v_and_b32_e32 v251, 6, v250
	v_and_b32_e32 v252, 7, v157
	v_xor_b32_e32 v251, v251, v252
	v_lshlrev_b32_e32 v251, 4, v251
	v_and_b32_e32 v252, 12, v250
	v_lshlrev_b32_e32 v252, 1, v252
	v_and_b32_e32 v253, 16, v250
	v_lshrrev_b32_e32 v253, 2, v253
	v_or_b32_e32 v252, v252, v253
	v_and_b32_e32 v253, 35, v250
	v_or_b32_e32 v250, v252, v253
	v_mul_u32_u24_e32 v250, 0x800, v250
	v_add_u32_e32 v166, v250, v251
	v_add_u32_e32 v166, 0x20000, v166
	s_add_u32 s12, s66, 0x40000
	global_load_lds_dwordx4 v166, s[66:67]
	s_addc_u32 s13, s67, 0
	s_add_i32 m0, s74, 0x14000
	v_lshl_add_u32 v164, v1, 11, v2
	v_lshrrev_b32_e32 v250, 3, v157
	v_and_b32_e32 v251, 6, v250
	v_and_b32_e32 v252, 7, v157
	v_xor_b32_e32 v251, v251, v252
	v_lshlrev_b32_e32 v251, 4, v251
	v_mul_u32_u24_e32 v250, 0x800, v250
	v_add_u32_e32 v164, v250, v251
	v_add_u32_e32 v164, 0x20000, v164
	global_load_lds_dwordx4 v162, s[12:13]
	s_add_i32 m0, s74, 0x16000
	s_add_u32 s68, s35, s10
	s_addc_u32 s69, s47, s11
	s_add_i32 s75, s74, 0x2000
	global_load_lds_dwordx4 v166, s[12:13]
	s_mov_b32 m0, s74
	s_add_u32 s10, s68, 0x40000
	global_load_lds_dwordx4 v160, s[68:69]
	s_mov_b32 m0, s75
	s_addc_u32 s11, s69, 0
	s_add_i32 s76, s74, 0x4000
	global_load_lds_dwordx4 v164, s[68:69]
	s_mov_b32 m0, s76
	s_add_i32 s77, s74, 0x6000
	global_load_lds_dwordx4 v160, s[10:11]
	s_mov_b32 m0, s77
	v_mov_b32_e32 v163, 0
	global_load_lds_dwordx4 v164, s[10:11]
	v_mov_b32_e32 v167, v163
	v_mov_b32_e32 v161, v163
	v_mov_b32_e32 v165, v163
	s_cmp_eq_u32 s9, 1
	s_mov_b32 s21, 0
	v_lshl_add_u64 v[6:7], s[66:67], 0, v[162:163]
	v_lshl_add_u64 v[4:5], s[66:67], 0, v[166:167]
	v_lshl_add_u64 v[0:1], s[68:69], 0, v[160:161]
	s_cselect_b64 s[22:23], -1, 0
	s_cmp_lg_u32 s9, 1
	v_lshl_add_u64 v[2:3], s[68:69], 0, v[164:165]
	s_cbranch_scc1 .LBB0_245
	s_barrier

.LBB0_248:
	s_add_i32 s90, s90, 1
	s_mul_i32 s3, s90, s80
	s_mul_hi_u32 s12, s90, s81
	s_add_i32 s12, s12, s3
	s_mul_i32 s3, s90, s81
	s_add_u32 s62, s3, s2
	s_addc_u32 s63, s12, s82
	v_cmp_gt_i64_e32 vcc, s[62:63], v[174:175]
	v_cmp_lt_i64_e64 s[12:13], s[62:63], v[172:173]
	s_cbranch_vccnz .LBB0_254
	s_cmp_eq_u32 s42, 0x100
	s_cbranch_scc0 .Lwgm_orig_1
	s_and_b32 s98, s2, 7
	s_lshr_b32 s99, s2, 3
	s_lshr_b32 s100, s90, 1
	s_lshl_b32 s100, s100, 2
	s_and_b32 s101, s99, 3
	s_add_i32 s60, s100, s101
	s_and_b32 s100, s90, 1
	s_lshl_b32 s100, s100, 3
	s_lshr_b32 s101, s99, 2
	s_add_i32 s58, s100, s101
	s_lshl_b32 s98, s98, 4
	s_add_i32 s60, s60, s98
	s_branch .LBB0_254
.Lwgm_orig_1:
	s_ashr_i32 s3, s62, 31
	s_lshr_b32 s3, s3, 29
	s_add_i32 s3, s62, s3
	s_and_b32 s15, s3, -8
	s_sub_i32 s15, s62, s15
	s_cmp_gt_i32 s15, -1
	s_mov_b64 s[58:59], -1
	s_cbranch_scc0 .LBB0_251
	s_lshl_b32 s60, s15, 8
	s_mov_b64 s[58:59], 0

.LBB0_517:
	s_or_b64 exec, exec, s[8:9]
	s_mov_b64 s[10:11], s[0:1]
	v_mov_b32_e32 v8, v157
	s_waitcnt lgkmcnt(0)
	v_cndmask_b32_e64 v0, 0, 1, s[24:25]
	s_barrier
	v_cmp_ne_u32_e64 s[8:9], 1, v0
	s_andn2_b64 vcc, exec, s[24:25]
	v_readfirstlane_b32 s24, v8
	s_cbranch_vccnz .LBB0_535
	v_lshlrev_b32_e32 v0, 4, v8
	v_add_u32_e32 v1, 0x2000, v0
	v_ashrrev_i32_e32 v2, 31, v1
	v_lshrrev_b32_e32 v2, 22, v2
	v_add_u32_e32 v2, v1, v2
	v_ashrrev_i32_e32 v9, 10, v2
	v_mul_i32_i24_e32 v2, 0x400, v9
	v_sub_u32_e32 v1, v1, v2
	v_lshrrev_b32_e32 v2, 4, v1
	v_bitop3_b32 v1, v2, v1, 32 bitop3:0x6c
	v_ashrrev_i32_e32 v2, 31, v1
	v_lshrrev_b32_e32 v2, 26, v2
	v_add_u32_e32 v2, v1, v2
	v_lshlrev_b32_e32 v3, 3, v9
	v_ashrrev_i32_e32 v10, 6, v2
	v_and_b32_e32 v3, -16, v3
	v_add_u32_e32 v3, v10, v3
	v_and_b32_e32 v4, 3, v10
	s_mov_b32 s12, 0x1fffe0
	v_lshrrev_b32_e32 v5, 2, v3
	v_lshlrev_b32_e32 v6, 1, v3
	v_and_b32_e32 v2, 0xc0, v2
	v_and_or_b32 v4, v3, s12, v4
	v_and_b32_e32 v5, 4, v5
	v_and_b32_e32 v6, 24, v6
	v_sub_u32_e32 v1, v1, v2
	v_mov_b32_e32 v2, 1
	v_or3_b32 v4, v4, v5, v6
	v_lshlrev_b32_e32 v5, 5, v9
	v_ashrrev_i16_sdwa v1, v2, sext(v1) dst_sel:DWORD dst_unused:UNUSED_PAD src0_sel:DWORD src1_sel:BYTE_0
	v_and_b32_e32 v5, 32, v5
	v_bfe_i32 v11, v1, 0, 16
	v_add_lshl_u32 v1, v5, v11, 1
	v_lshl_add_u32 v128, v4, 11, v1
	v_lshrrev_b32_e32 v250, 3, v157
	v_and_b32_e32 v251, 6, v250
	v_and_b32_e32 v252, 7, v157
	v_xor_b32_e32 v251, v251, v252
	v_lshlrev_b32_e32 v251, 4, v251
	v_and_b32_e32 v252, 12, v250
	v_lshlrev_b32_e32 v252, 1, v252
	v_and_b32_e32 v253, 16, v250
	v_lshrrev_b32_e32 v253, 2, v253
	v_or_b32_e32 v252, v252, v253
	v_and_b32_e32 v253, 35, v250
	v_or_b32_e32 v250, v252, v253
	v_mul_u32_u24_e32 v250, 0x800, v250
	v_add_u32_e32 v128, v250, v251
	v_add_u32_e32 v128, 0x20000, v128
	v_lshl_add_u32 v130, v3, 11, v1
	v_lshrrev_b32_e32 v250, 3, v157
	v_and_b32_e32 v251, 6, v250
	v_and_b32_e32 v252, 7, v157
	v_xor_b32_e32 v251, v251, v252
	v_lshlrev_b32_e32 v251, 4, v251
	v_mul_u32_u24_e32 v250, 0x800, v250
	v_add_u32_e32 v130, v250, v251
	v_add_u32_e32 v130, 0x20000, v130
	v_bfe_i32 v1, v8, 27, 1
	v_lshrrev_b32_e32 v1, 22, v1
	v_add_u32_e32 v1, v0, v1
	s_load_dwordx2 s[10:11], s[10:11], 0x80
	v_and_b32_e32 v1, 0xfffffc00, v1
	v_sub_u32_e32 v0, v0, v1
	v_lshrrev_b32_e32 v1, 4, v0
	v_ashrrev_i32_e32 v3, 31, v8
	v_bitop3_b32 v0, v1, v0, 32 bitop3:0x6c
	v_lshrrev_b32_e32 v3, 26, v3
	v_ashrrev_i32_e32 v1, 31, v0
	v_add_u32_e32 v3, v8, v3
	s_waitcnt lgkmcnt(0)
	s_add_u32 s3, s10, 0x6000000
	v_lshrrev_b32_e32 v1, 26, v1
	v_ashrrev_i32_e32 v13, 6, v3
	s_addc_u32 s35, s11, 0
	v_add_u32_e32 v1, v0, v1
	v_lshlrev_b32_e32 v3, 3, v13
	s_add_u32 s52, s10, 0xf00000
	v_ashrrev_i32_e32 v12, 6, v1
	v_and_b32_e32 v3, -16, v3
	s_addc_u32 s53, s11, 0
	v_add_u32_e32 v3, v12, v3
	v_and_b32_e32 v4, 3, v12
	s_ashr_i32 s55, s2, 31
	v_and_or_b32 v4, v3, s12, v4
	s_lshr_b32 s12, s55, 29
	s_add_i32 s12, s2, s12
	s_ashr_i32 s23, s24, 6
	s_ashr_i32 s13, s12, 3
	s_and_b32 s12, s12, -8
	s_ashr_i32 s25, s24, 8
	s_lshl_b32 s54, s23, 10
	s_sub_i32 s12, s2, s12
	s_cmp_lt_i32 s12, 0
	s_movk_i32 s56, 0x161
	s_cselect_b32 s14, s56, 0x160
	s_mul_i32 s12, s14, s12
	s_add_i32 s12, s12, s13
	s_mul_hi_i32 s13, s12, 0x2e8ba2e9
	s_lshr_b32 s14, s13, 31
	s_ashr_i32 s13, s13, 3
	s_add_i32 s13, s13, s14
	s_lshl_b32 s14, s13, 1
	s_mul_i32 s13, s13, 44
	s_sub_i32 s12, s12, s13
	s_bfe_u32 s13, s12, 0x10007
	s_add_i32 s13, s12, s13
	s_bfe_i32 s15, s13, 0x80000
	s_and_b32 s13, s13, 0xfe
	s_sub_i32 s12, s12, s13
	s_sext_i32_i16 s15, s15
	s_sext_i32_i8 s12, s12
	v_lshrrev_b32_e32 v5, 2, v3
	v_lshlrev_b32_e32 v6, 1, v3
	v_and_b32_e32 v1, 0xc0, v1
	s_lshr_b32 s22, s15, 1
	s_add_i32 s46, s14, s12
	s_cmp_eq_u32 s42, 0x100
	s_cbranch_scc0 .Lwgm_p_2
	s_lshr_b32 s99, s2, 3
	s_and_b32 s46, s99, 3
	s_lshr_b32 s22, s99, 2
	s_and_b32 s98, s2, 7
	s_lshl_b32 s98, s98, 4
	s_add_i32 s46, s46, s98
.Lwgm_p_2:
	v_and_b32_e32 v5, 4, v5
	v_and_b32_e32 v6, 24, v6
	v_sub_u32_e32 v0, v0, v1
	s_ashr_i32 s47, s46, 31
	s_bfe_i64 s[14:15], s[22:23], 0x100000
	v_or3_b32 v4, v4, v5, v6
	v_lshlrev_b32_e32 v5, 5, v13
	v_ashrrev_i16_sdwa v0, v2, sext(v0) dst_sel:DWORD dst_unused:UNUSED_PAD src0_sel:DWORD src1_sel:BYTE_0
	s_lshl_b64 s[12:13], s[46:47], 19
	s_lshl_b64 s[14:15], s[14:15], 19
	v_and_b32_e32 v5, 32, v5
	v_bfe_i32 v14, v0, 0, 16
	s_add_u32 s48, s52, s14
	v_add_lshl_u32 v0, v5, v14, 1
	s_addc_u32 s49, s53, s15
	s_add_i32 s57, s54, 0
	v_lshl_add_u32 v132, v4, 11, v0
	v_lshrrev_b32_e32 v250, 3, v157
	v_and_b32_e32 v251, 6, v250
	v_and_b32_e32 v252, 7, v157
	v_xor_b32_e32 v251, v251, v252
	v_lshlrev_b32_e32 v251, 4, v251
	v_and_b32_e32 v252, 12, v250
	v_lshlrev_b32_e32 v252, 1, v252
	v_and_b32_e32 v253, 16, v250
	v_lshrrev_b32_e32 v253, 2, v253
	v_or_b32_e32 v252, v252, v253
	v_and_b32_e32 v253, 35, v250
	v_or_b32_e32 v250, v252, v253
	v_mul_u32_u24_e32 v250, 0x800, v250
	v_add_u32_e32 v132, v250, v251
	s_add_i32 m0, s57, 0x10000
	v_lshl_add_u32 v134, v3, 11, v0
	v_lshrrev_b32_e32 v250, 3, v157
	v_and_b32_e32 v251, 6, v250
	v_and_b32_e32 v252, 7, v157
	v_xor_b32_e32 v251, v251, v252
	v_lshlrev_b32_e32 v251, 4, v251
	v_mul_u32_u24_e32 v250, 0x800, v250
	v_add_u32_e32 v134, v250, v251
	global_load_lds_dwordx4 v132, s[48:49]
	s_add_i32 m0, s57, 0x12000
	s_add_u32 s14, s48, 0x40000
	global_load_lds_dwordx4 v128, s[48:49]
	s_addc_u32 s15, s49, 0
	s_add_i32 m0, s57, 0x14000
	v_mov_b32_e32 v133, 0
	global_load_lds_dwordx4 v132, s[14:15]
	s_add_i32 m0, s57, 0x16000
	s_add_u32 s50, s3, s12
	s_addc_u32 s51, s35, s13
	s_add_i32 s58, s57, 0x2000
	global_load_lds_dwordx4 v128, s[14:15]
	s_mov_b32 m0, s57
	s_add_u32 s12, s50, 0x40000
	global_load_lds_dwordx4 v134, s[50:51]
	s_mov_b32 m0, s58
	s_addc_u32 s13, s51, 0
	s_add_i32 s59, s57, 0x4000
	global_load_lds_dwordx4 v130, s[50:51]
	s_mov_b32 m0, s59
	s_add_i32 s60, s57, 0x6000
	global_load_lds_dwordx4 v134, s[12:13]
	s_mov_b32 m0, s60
	v_mov_b32_e32 v129, v133
	global_load_lds_dwordx4 v130, s[12:13]
	v_mov_b32_e32 v135, v133
	v_mov_b32_e32 v131, v133
	s_cmp_eq_u32 s25, 1
	s_mov_b32 s61, 0
	v_lshl_add_u64 v[6:7], s[48:49], 0, v[132:133]
	v_lshl_add_u64 v[4:5], s[48:49], 0, v[128:129]
	v_lshl_add_u64 v[0:1], s[50:51], 0, v[134:135]
	s_cselect_b64 s[12:13], -1, 0
	s_cmp_lg_u32 s25, 1
	v_lshl_add_u64 v[2:3], s[50:51], 0, v[130:131]
	s_cbranch_scc1 .LBB0_520
	s_barrier

.LBB0_523:
	s_add_i32 s61, s61, 1
	s_mul_i32 s10, s61, s64
	s_mul_hi_u32 s11, s61, s65
	s_add_i32 s11, s11, s10
	s_mul_i32 s10, s61, s65
	s_add_u32 s30, s10, s2
	s_addc_u32 s31, s11, s55
	v_cmp_gt_i64_e32 vcc, s[30:31], v[142:143]
	v_cmp_lt_i64_e64 s[10:11], s[30:31], v[140:141]
	s_cbranch_vccnz .LBB0_525
	s_cmp_eq_u32 s42, 0x100
	s_cbranch_scc0 .Lwgm_orig_2
	s_and_b32 s98, s2, 7
	s_lshr_b32 s99, s2, 3
	s_cmp_lt_u32 s61, 8
	s_cbranch_scc0 .Lwgm_tail_2
	s_lshr_b32 s100, s61, 1
	s_lshl_b32 s100, s100, 2
	s_and_b32 s101, s99, 3
	s_add_i32 s28, s100, s101
	s_and_b32 s100, s61, 1
	s_lshl_b32 s100, s100, 3
	s_lshr_b32 s101, s99, 2
	s_add_i32 s26, s100, s101
	s_branch .Lwgm_join_2
.Lwgm_tail_2:
	s_sub_i32 s100, s61, 8
	s_lshl_b32 s100, s100, 5
	s_add_i32 s100, s100, s99
	s_mul_hi_u32 s28, s100, 0x2aaaaaab
	s_mul_i32 s101, s28, 6
	s_sub_i32 s101, s100, s101
	s_add_i32 s26, s101, 16
.Lwgm_join_2:
	s_lshl_b32 s98, s98, 4
	s_add_i32 s28, s28, s98
	s_branch .LBB0_525
.Lwgm_orig_2:
	s_ashr_i32 s26, s30, 31
	s_lshr_b32 s26, s26, 29
	s_add_i32 s26, s30, s26
	s_ashr_i32 s27, s26, 3
	s_and_b32 s26, s26, -8
	s_sub_i32 s26, s30, s26
	s_cmp_lt_i32 s26, 0
	s_cselect_b32 s28, s56, 0x160
	s_mul_i32 s26, s28, s26
	s_add_i32 s26, s26, s27
	s_mul_hi_i32 s27, s26, 0x2e8ba2e9
	s_lshr_b32 s28, s27, 31
	s_ashr_i32 s27, s27, 3
	s_add_i32 s27, s27, s28
	s_lshl_b32 s28, s27, 1
	s_sub_i32 s29, 0x80, s28
	s_min_i32 s29, s29, 2
	s_abs_i32 s30, s29
	v_cvt_f32_u32_e32 v0, s30
	s_sub_i32 s44, 0, s30
	s_mul_i32 s27, s27, 44
	s_sub_i32 s27, s26, s27
	v_rcp_iflag_f32_e32 v0, v0
	s_abs_i32 s26, s27
	s_xor_b32 s31, s27, s29
	s_ashr_i32 s31, s31, 31
	v_mul_f32_e32 v0, 0x4f7ffffe, v0
	v_cvt_u32_f32_e32 v0, v0
	s_nop 0
	v_readfirstlane_b32 s45, v0
	s_mul_i32 s44, s44, s45
	s_mul_hi_u32 s44, s45, s44
	s_add_i32 s45, s45, s44
	s_mul_hi_u32 s44, s26, s45
	s_mul_i32 s45, s44, s30
	s_sub_i32 s26, s26, s45
	s_add_i32 s47, s44, 1
	s_sub_i32 s45, s26, s30
	s_cmp_ge_u32 s26, s30
	s_cselect_b32 s44, s47, s44
	s_cselect_b32 s26, s45, s26
	s_add_i32 s45, s44, 1
	s_cmp_ge_u32 s26, s30
	s_cselect_b32 s26, s45, s44
	s_xor_b32 s26, s26, s31
	s_sub_i32 s26, s26, s31
	s_mul_i32 s29, s26, s29
	s_sub_i32 s27, s27, s29
	s_add_i32 s28, s27, s28

.LBB0_687:
	s_or_b64 exec, exec, s[10:11]
	s_mov_b64 s[10:11], s[0:1]
	v_mov_b32_e32 v8, v157
	s_waitcnt lgkmcnt(0)
	s_barrier
	s_and_b64 vcc, exec, s[8:9]
	v_readfirstlane_b32 s24, v8
	s_cbranch_vccnz .LBB0_705
	v_lshlrev_b32_e32 v0, 4, v8
	v_add_u32_e32 v1, 0x2000, v0
	v_ashrrev_i32_e32 v2, 31, v1
	v_lshrrev_b32_e32 v2, 22, v2
	v_add_u32_e32 v2, v1, v2
	v_ashrrev_i32_e32 v9, 10, v2
	v_mul_i32_i24_e32 v2, 0x400, v9
	v_sub_u32_e32 v1, v1, v2
	v_lshrrev_b32_e32 v2, 4, v1
	v_bitop3_b32 v1, v2, v1, 32 bitop3:0x6c
	v_ashrrev_i32_e32 v2, 31, v1
	v_lshrrev_b32_e32 v2, 26, v2
	v_add_u32_e32 v2, v1, v2
	v_lshlrev_b32_e32 v3, 3, v9
	v_ashrrev_i32_e32 v10, 6, v2
	v_and_b32_e32 v3, -16, v3
	v_add_u32_e32 v3, v10, v3
	v_and_b32_e32 v4, 3, v10
	s_mov_b32 s12, 0x1fffe0
	v_lshrrev_b32_e32 v5, 2, v3
	v_lshlrev_b32_e32 v6, 1, v3
	v_and_b32_e32 v2, 0xc0, v2
	v_and_or_b32 v4, v3, s12, v4
	v_and_b32_e32 v5, 4, v5
	v_and_b32_e32 v6, 24, v6
	v_sub_u32_e32 v1, v1, v2
	v_mov_b32_e32 v2, 1
	v_or3_b32 v4, v4, v5, v6
	v_lshlrev_b32_e32 v5, 5, v9
	v_ashrrev_i16_sdwa v1, v2, sext(v1) dst_sel:DWORD dst_unused:UNUSED_PAD src0_sel:DWORD src1_sel:BYTE_0
	v_and_b32_e32 v5, 32, v5
	v_bfe_i32 v11, v1, 0, 16
	v_add_lshl_u32 v1, v5, v11, 1
	v_lshl_add_u32 v128, v4, 11, v1
	v_lshrrev_b32_e32 v250, 3, v157
	v_and_b32_e32 v251, 6, v250
	v_and_b32_e32 v252, 7, v157
	v_xor_b32_e32 v251, v251, v252
	v_lshlrev_b32_e32 v251, 4, v251
	v_and_b32_e32 v252, 12, v250
	v_lshlrev_b32_e32 v252, 1, v252
	v_and_b32_e32 v253, 16, v250
	v_lshrrev_b32_e32 v253, 2, v253
	v_or_b32_e32 v252, v252, v253
	v_and_b32_e32 v253, 35, v250
	v_or_b32_e32 v250, v252, v253
	v_mul_u32_u24_e32 v250, 0x800, v250
	v_add_u32_e32 v128, v250, v251
	v_add_u32_e32 v128, 0x20000, v128
	v_lshl_add_u32 v130, v3, 11, v1
	v_lshrrev_b32_e32 v250, 3, v157
	v_and_b32_e32 v251, 6, v250
	v_and_b32_e32 v252, 7, v157
	v_xor_b32_e32 v251, v251, v252
	v_lshlrev_b32_e32 v251, 4, v251
	v_mul_u32_u24_e32 v250, 0x800, v250
	v_add_u32_e32 v130, v250, v251
	v_add_u32_e32 v130, 0x20000, v130
	v_bfe_i32 v1, v8, 27, 1
	v_lshrrev_b32_e32 v1, 22, v1
	v_add_u32_e32 v1, v0, v1
	s_load_dwordx2 s[10:11], s[10:11], 0x80
	v_and_b32_e32 v1, 0xfffffc00, v1
	v_sub_u32_e32 v0, v0, v1
	v_lshrrev_b32_e32 v1, 4, v0
	v_ashrrev_i32_e32 v3, 31, v8
	v_bitop3_b32 v0, v1, v0, 32 bitop3:0x6c
	v_lshrrev_b32_e32 v3, 26, v3
	v_ashrrev_i32_e32 v1, 31, v0
	v_add_u32_e32 v3, v8, v3
	s_waitcnt lgkmcnt(0)
	s_add_u32 s3, s10, 0x6000000
	v_lshrrev_b32_e32 v1, 26, v1
	v_ashrrev_i32_e32 v13, 6, v3
	s_addc_u32 s35, s11, 0
	v_add_u32_e32 v1, v0, v1
	v_lshlrev_b32_e32 v3, 3, v13
	s_add_u32 s52, s10, 0x1a00000
	v_ashrrev_i32_e32 v12, 6, v1
	v_and_b32_e32 v3, -16, v3
	s_addc_u32 s53, s11, 0
	v_add_u32_e32 v3, v12, v3
	v_and_b32_e32 v4, 3, v12
	s_ashr_i32 s55, s2, 31
	v_and_or_b32 v4, v3, s12, v4
	s_lshr_b32 s12, s55, 29
	s_add_i32 s12, s2, s12
	s_ashr_i32 s23, s24, 6
	s_ashr_i32 s13, s12, 3
	s_and_b32 s12, s12, -8
	s_ashr_i32 s25, s24, 8
	s_lshl_b32 s54, s23, 10
	s_sub_i32 s12, s2, s12
	s_cmp_lt_i32 s12, 0
	s_movk_i32 s56, 0x161
	s_cselect_b32 s14, s56, 0x160
	s_mul_i32 s12, s14, s12
	s_add_i32 s12, s12, s13
	s_mul_hi_i32 s13, s12, 0x2e8ba2e9
	s_lshr_b32 s14, s13, 31
	s_ashr_i32 s13, s13, 3
	s_add_i32 s13, s13, s14
	s_lshl_b32 s14, s13, 1
	s_mul_i32 s13, s13, 44
	s_sub_i32 s12, s12, s13
	s_bfe_u32 s13, s12, 0x10007
	s_add_i32 s13, s12, s13
	s_bfe_i32 s15, s13, 0x80000
	s_and_b32 s13, s13, 0xfe
	s_sub_i32 s12, s12, s13
	s_sext_i32_i16 s15, s15
	s_sext_i32_i8 s12, s12
	v_lshrrev_b32_e32 v5, 2, v3
	v_lshlrev_b32_e32 v6, 1, v3
	v_and_b32_e32 v1, 0xc0, v1
	s_lshr_b32 s22, s15, 1
	s_add_i32 s46, s14, s12
	s_cmp_eq_u32 s42, 0x100
	s_cbranch_scc0 .Lwgm_p_3
	s_lshr_b32 s99, s2, 3
	s_and_b32 s46, s99, 3
	s_lshr_b32 s22, s99, 2
	s_and_b32 s98, s2, 7
	s_lshl_b32 s98, s98, 4
	s_add_i32 s46, s46, s98

.LBB0_1088:
	s_or_b64 exec, exec, s[6:7]
	s_mov_b64 s[6:7], s[0:1]
	v_mov_b32_e32 v8, v157
	s_waitcnt lgkmcnt(0)
	s_barrier
	s_and_b64 vcc, exec, s[8:9]
	v_readfirstlane_b32 s20, v8
	s_cbranch_vccnz .LBB0_1106
	v_lshlrev_b32_e32 v0, 4, v8
	v_add_u32_e32 v1, 0x2000, v0
	v_ashrrev_i32_e32 v2, 31, v1
	v_lshrrev_b32_e32 v2, 22, v2
	v_add_u32_e32 v2, v1, v2
	v_ashrrev_i32_e32 v9, 10, v2
	v_mul_i32_i24_e32 v2, 0x400, v9
	v_sub_u32_e32 v1, v1, v2
	v_lshrrev_b32_e32 v2, 4, v1
	v_bitop3_b32 v1, v2, v1, 32 bitop3:0x6c
	v_ashrrev_i32_e32 v2, 31, v1
	v_lshrrev_b32_e32 v2, 26, v2
	v_add_u32_e32 v2, v1, v2
	v_lshlrev_b32_e32 v3, 3, v9
	v_ashrrev_i32_e32 v10, 6, v2
	v_and_b32_e32 v3, -16, v3
	v_add_u32_e32 v3, v10, v3
	v_and_b32_e32 v4, 3, v10
	s_mov_b32 s8, 0x1fffe0
	v_lshrrev_b32_e32 v5, 2, v3
	v_lshlrev_b32_e32 v6, 1, v3
	v_and_b32_e32 v2, 0xc0, v2
	v_and_or_b32 v4, v3, s8, v4
	v_and_b32_e32 v5, 4, v5
	v_and_b32_e32 v6, 24, v6
	v_sub_u32_e32 v1, v1, v2
	v_mov_b32_e32 v2, 1
	v_or3_b32 v4, v4, v5, v6
	v_lshlrev_b32_e32 v5, 5, v9
	v_ashrrev_i16_sdwa v1, v2, sext(v1) dst_sel:DWORD dst_unused:UNUSED_PAD src0_sel:DWORD src1_sel:BYTE_0
	v_and_b32_e32 v5, 32, v5
	v_bfe_i32 v11, v1, 0, 16
	v_add_lshl_u32 v1, v5, v11, 1
	v_lshl_add_u32 v128, v4, 11, v1
	v_lshrrev_b32_e32 v250, 3, v157
	v_and_b32_e32 v251, 6, v250
	v_and_b32_e32 v252, 7, v157
	v_xor_b32_e32 v251, v251, v252
	v_lshlrev_b32_e32 v251, 4, v251
	v_and_b32_e32 v252, 12, v250
	v_lshlrev_b32_e32 v252, 1, v252
	v_and_b32_e32 v253, 16, v250
	v_lshrrev_b32_e32 v253, 2, v253
	v_or_b32_e32 v252, v252, v253
	v_and_b32_e32 v253, 35, v250
	v_or_b32_e32 v250, v252, v253
	v_mul_u32_u24_e32 v250, 0x800, v250
	v_add_u32_e32 v128, v250, v251
	v_add_u32_e32 v128, 0x20000, v128
	v_lshl_add_u32 v130, v3, 11, v1
	v_lshrrev_b32_e32 v250, 3, v157
	v_and_b32_e32 v251, 6, v250
	v_and_b32_e32 v252, 7, v157
	v_xor_b32_e32 v251, v251, v252
	v_lshlrev_b32_e32 v251, 4, v251
	v_mul_u32_u24_e32 v250, 0x800, v250
	v_add_u32_e32 v130, v250, v251
	v_add_u32_e32 v130, 0x20000, v130
	v_bfe_i32 v1, v8, 27, 1
	v_lshrrev_b32_e32 v1, 22, v1
	v_add_u32_e32 v1, v0, v1
	s_load_dwordx2 s[6:7], s[6:7], 0x80
	v_and_b32_e32 v1, 0xfffffc00, v1
	v_sub_u32_e32 v0, v0, v1
	v_lshrrev_b32_e32 v1, 4, v0
	v_ashrrev_i32_e32 v3, 31, v8
	v_bitop3_b32 v0, v1, v0, 32 bitop3:0x6c
	v_lshrrev_b32_e32 v3, 26, v3
	v_ashrrev_i32_e32 v1, 31, v0
	v_add_u32_e32 v3, v8, v3
	s_waitcnt lgkmcnt(0)
	s_add_u32 s3, s6, 0x6000000
	v_lshrrev_b32_e32 v1, 26, v1
	v_ashrrev_i32_e32 v13, 6, v3
	s_addc_u32 s33, s7, 0
	v_add_u32_e32 v1, v0, v1
	v_lshlrev_b32_e32 v3, 3, v13
	s_add_u32 s35, s6, 0x2500000
	v_ashrrev_i32_e32 v12, 6, v1
	v_and_b32_e32 v3, -16, v3
	s_addc_u32 s48, s7, 0
	v_add_u32_e32 v3, v12, v3
	v_and_b32_e32 v4, 3, v12
	s_ashr_i32 s50, s2, 31
	v_and_or_b32 v4, v3, s8, v4
	s_lshr_b32 s8, s50, 29
	s_add_i32 s8, s2, s8
	s_ashr_i32 s17, s20, 6
	s_ashr_i32 s9, s8, 3
	s_and_b32 s8, s8, -8
	s_ashr_i32 s21, s20, 8
	s_lshl_b32 s49, s17, 10
	s_sub_i32 s8, s2, s8
	s_cmp_lt_i32 s8, 0
	s_movk_i32 s51, 0x161
	s_cselect_b32 s10, s51, 0x160
	s_mul_i32 s8, s10, s8
	s_add_i32 s8, s8, s9
	s_mul_hi_i32 s9, s8, 0x2e8ba2e9
	s_lshr_b32 s10, s9, 31
	s_ashr_i32 s9, s9, 3
	s_add_i32 s9, s9, s10
	s_lshl_b32 s10, s9, 1
	s_mul_i32 s9, s9, 44
	s_sub_i32 s8, s8, s9
	s_bfe_u32 s9, s8, 0x10007
	s_add_i32 s9, s8, s9
	s_bfe_i32 s11, s9, 0x80000
	s_and_b32 s9, s9, 0xfe
	s_sub_i32 s8, s8, s9
	s_sext_i32_i16 s11, s11
	s_sext_i32_i8 s8, s8
	v_lshrrev_b32_e32 v5, 2, v3
	v_lshlrev_b32_e32 v6, 1, v3
	v_and_b32_e32 v1, 0xc0, v1
	s_lshr_b32 s16, s11, 1
	s_add_i32 s30, s10, s8
	s_cmp_eq_u32 s42, 0x100
	s_cbranch_scc0 .Lwgm_p_4
	s_lshr_b32 s99, s2, 3
	s_and_b32 s30, s99, 3
	s_lshr_b32 s16, s99, 2
	s_and_b32 s98, s2, 7
	s_lshl_b32 s98, s98, 4
	s_add_i32 s30, s30, s98
.Lwgm_p_4:
	v_and_b32_e32 v5, 4, v5
	v_and_b32_e32 v6, 24, v6
	v_sub_u32_e32 v0, v0, v1
	s_ashr_i32 s31, s30, 31
	s_bfe_i64 s[10:11], s[16:17], 0x100000
	v_or3_b32 v4, v4, v5, v6
	v_lshlrev_b32_e32 v5, 5, v13
	v_ashrrev_i16_sdwa v0, v2, sext(v0) dst_sel:DWORD dst_unused:UNUSED_PAD src0_sel:DWORD src1_sel:BYTE_0
	s_lshl_b64 s[8:9], s[30:31], 19
	s_lshl_b64 s[10:11], s[10:11], 19
	v_and_b32_e32 v5, 32, v5
	v_bfe_i32 v14, v0, 0, 16
	s_add_u32 s44, s35, s10
	v_add_lshl_u32 v0, v5, v14, 1
	s_addc_u32 s45, s48, s11
	s_add_i32 s52, s49, 0
	v_lshl_add_u32 v132, v4, 11, v0
	v_lshrrev_b32_e32 v250, 3, v157
	v_and_b32_e32 v251, 6, v250
	v_and_b32_e32 v252, 7, v157
	v_xor_b32_e32 v251, v251, v252
	v_lshlrev_b32_e32 v251, 4, v251
	v_and_b32_e32 v252, 12, v250
	v_lshlrev_b32_e32 v252, 1, v252
	v_and_b32_e32 v253, 16, v250
	v_lshrrev_b32_e32 v253, 2, v253
	v_or_b32_e32 v252, v252, v253
	v_and_b32_e32 v253, 35, v250
	v_or_b32_e32 v250, v252, v253
	v_mul_u32_u24_e32 v250, 0x800, v250
	v_add_u32_e32 v132, v250, v251
	s_add_i32 m0, s52, 0x10000
	v_lshl_add_u32 v134, v3, 11, v0
	v_lshrrev_b32_e32 v250, 3, v157
	v_and_b32_e32 v251, 6, v250
	v_and_b32_e32 v252, 7, v157
	v_xor_b32_e32 v251, v251, v252
	v_lshlrev_b32_e32 v251, 4, v251
	v_mul_u32_u24_e32 v250, 0x800, v250
	v_add_u32_e32 v134, v250, v251
	global_load_lds_dwordx4 v132, s[44:45]
	s_add_i32 m0, s52, 0x12000
	s_add_u32 s10, s44, 0x40000
	global_load_lds_dwordx4 v128, s[44:45]
	s_addc_u32 s11, s45, 0
	s_add_i32 m0, s52, 0x14000
	v_mov_b32_e32 v133, 0
	global_load_lds_dwordx4 v132, s[10:11]
	s_add_i32 m0, s52, 0x16000
	s_add_u32 s46, s3, s8
	s_addc_u32 s47, s33, s9
	s_add_i32 s53, s52, 0x2000
	global_load_lds_dwordx4 v128, s[10:11]
	s_mov_b32 m0, s52
	s_add_u32 s8, s46, 0x40000
	global_load_lds_dwordx4 v134, s[46:47]
	s_mov_b32 m0, s53
	s_addc_u32 s9, s47, 0
	s_add_i32 s54, s52, 0x4000
	global_load_lds_dwordx4 v130, s[46:47]
	s_mov_b32 m0, s54
	s_add_i32 s55, s52, 0x6000
	global_load_lds_dwordx4 v134, s[8:9]
	s_mov_b32 m0, s55
	v_mov_b32_e32 v129, v133
	global_load_lds_dwordx4 v130, s[8:9]
	v_mov_b32_e32 v135, v133
	v_mov_b32_e32 v131, v133
	s_cmp_eq_u32 s21, 1
	s_mov_b32 s56, 0
	v_lshl_add_u64 v[6:7], s[44:45], 0, v[132:133]
	v_lshl_add_u64 v[4:5], s[44:45], 0, v[128:129]
	v_lshl_add_u64 v[0:1], s[46:47], 0, v[134:135]
	s_cselect_b64 s[8:9], -1, 0
	s_cmp_lg_u32 s21, 1
	v_lshl_add_u64 v[2:3], s[46:47], 0, v[130:131]
	s_cbranch_scc1 .LBB0_1091
	s_barrier

.LBB0_1094:
	s_add_i32 s56, s56, 1
	s_mul_i32 s6, s56, s59
	s_mul_hi_u32 s7, s56, s60
	s_add_i32 s7, s7, s6
	s_mul_i32 s6, s56, s60
	s_add_u32 s26, s6, s2
	s_addc_u32 s27, s7, s50
	v_cmp_gt_i64_e32 vcc, s[26:27], v[142:143]
	v_cmp_lt_i64_e64 s[6:7], s[26:27], v[140:141]
	s_cbranch_vccnz .LBB0_1096
	s_cmp_eq_u32 s42, 0x100
	s_cbranch_scc0 .Lwgm_orig_4
	s_and_b32 s98, s2, 7
	s_lshr_b32 s99, s2, 3
	s_cmp_lt_u32 s56, 8
	s_cbranch_scc0 .Lwgm_tail_4
	s_lshr_b32 s100, s56, 1
	s_lshl_b32 s100, s100, 2
	s_and_b32 s101, s99, 3
	s_add_i32 s24, s100, s101
	s_and_b32 s100, s56, 1
	s_lshl_b32 s100, s100, 3
	s_lshr_b32 s101, s99, 2
	s_add_i32 s22, s100, s101
	s_branch .Lwgm_join_4
.Lwgm_tail_4:
	s_sub_i32 s100, s56, 8
	s_lshl_b32 s100, s100, 5
	s_add_i32 s100, s100, s99
	s_mul_hi_u32 s24, s100, 0x2aaaaaab
	s_mul_i32 s101, s24, 6
	s_sub_i32 s101, s100, s101
	s_add_i32 s22, s101, 16
.Lwgm_join_4:
	s_lshl_b32 s98, s98, 4
	s_add_i32 s24, s24, s98
	s_branch .LBB0_1096
.Lwgm_orig_4:
	s_ashr_i32 s22, s26, 31
	s_lshr_b32 s22, s22, 29
	s_add_i32 s22, s26, s22
	s_ashr_i32 s23, s22, 3
	s_and_b32 s22, s22, -8
	s_sub_i32 s22, s26, s22
	s_cmp_lt_i32 s22, 0
	s_cselect_b32 s24, s51, 0x160
	s_mul_i32 s22, s24, s22
	s_add_i32 s22, s22, s23
	s_mul_hi_i32 s23, s22, 0x2e8ba2e9
	s_lshr_b32 s24, s23, 31
	s_ashr_i32 s23, s23, 3
	s_add_i32 s23, s23, s24
	s_lshl_b32 s24, s23, 1
	s_sub_i32 s25, 0x80, s24
	s_min_i32 s25, s25, 2
	s_abs_i32 s26, s25
	v_cvt_f32_u32_e32 v0, s26
	s_sub_i32 s28, 0, s26
	s_mul_i32 s23, s23, 44
	s_sub_i32 s23, s22, s23
	v_rcp_iflag_f32_e32 v0, v0
	s_abs_i32 s22, s23
	s_xor_b32 s27, s23, s25
	s_ashr_i32 s27, s27, 31
	v_mul_f32_e32 v0, 0x4f7ffffe, v0
	v_cvt_u32_f32_e32 v0, v0
	s_nop 0
	v_readfirstlane_b32 s29, v0
	s_mul_i32 s28, s28, s29
	s_mul_hi_u32 s28, s29, s28
	s_add_i32 s29, s29, s28
	s_mul_hi_u32 s28, s22, s29
	s_mul_i32 s29, s28, s26
	s_sub_i32 s22, s22, s29
	s_add_i32 s31, s28, 1
	s_sub_i32 s29, s22, s26
	s_cmp_ge_u32 s22, s26
	s_cselect_b32 s28, s31, s28
	s_cselect_b32 s22, s29, s22
	s_add_i32 s29, s28, 1
	s_cmp_ge_u32 s22, s26
	s_cselect_b32 s22, s29, s28
	s_xor_b32 s22, s22, s27
	s_sub_i32 s22, s22, s27
	s_mul_i32 s25, s22, s25
	s_sub_i32 s23, s23, s25
	s_add_i32 s24, s23, s24

	.amdhsa_kernel _ZN2mk14fwd_megakernelILi0ELi16EEEvNS_4ArgsE
		.amdhsa_group_segment_fixed_size 0
		.amdhsa_private_segment_fixed_size 0
		.amdhsa_kernarg_size 392
		.amdhsa_user_sgpr_count 2
		.amdhsa_user_sgpr_dispatch_ptr 0
		.amdhsa_user_sgpr_queue_ptr 0
		.amdhsa_user_sgpr_kernarg_segment_ptr 1
		.amdhsa_user_sgpr_dispatch_id 0
		.amdhsa_user_sgpr_kernarg_preload_length 0
		.amdhsa_user_sgpr_kernarg_preload_offset 0
		.amdhsa_user_sgpr_private_segment_size 0
		.amdhsa_uses_dynamic_stack 0
		.amdhsa_enable_private_segment 0
		.amdhsa_system_sgpr_workgroup_id_x 1
		.amdhsa_system_sgpr_workgroup_id_y 0
		.amdhsa_system_sgpr_workgroup_id_z 0
		.amdhsa_system_sgpr_workgroup_info 0
		.amdhsa_system_vgpr_workitem_id 2
		.amdhsa_next_free_vgpr 256
		.amdhsa_next_free_sgpr 102
		.amdhsa_accum_offset 256
		.amdhsa_reserve_vcc 1
		.amdhsa_float_round_mode_32 0
		.amdhsa_float_round_mode_16_64 0
		.amdhsa_float_denorm_mode_32 3
		.amdhsa_float_denorm_mode_16_64 3
		.amdhsa_dx10_clamp 1
		.amdhsa_ieee_mode 1
		.amdhsa_fp16_overflow 0
		.amdhsa_tg_split 0
		.amdhsa_exception_fp_ieee_invalid_op 0
		.amdhsa_exception_fp_denorm_src 0
		.amdhsa_exception_fp_ieee_div_zero 0
		.amdhsa_exception_fp_ieee_overflow 0
		.amdhsa_exception_fp_ieee_underflow 0
		.amdhsa_exception_fp_ieee_inexact 0
		.amdhsa_exception_int_div_zero 0
	.end_amdhsa_kernel

amdhsa.kernels:
  - .agpr_count:     0
    .args:
      - .offset:         0
        .size:           136
        .value_kind:     by_value
      - .offset:         136
        .size:           4
        .value_kind:     hidden_block_count_x
      - .offset:         140
        .size:           4
        .value_kind:     hidden_block_count_y
      - .offset:         144
        .size:           4
        .value_kind:     hidden_block_count_z
      - .offset:         148
        .size:           2
        .value_kind:     hidden_group_size_x
      - .offset:         150
        .size:           2
        .value_kind:     hidden_group_size_y
      - .offset:         152
        .size:           2
        .value_kind:     hidden_group_size_z
      - .offset:         154
        .size:           2
        .value_kind:     hidden_remainder_x
      - .offset:         156
        .size:           2
        .value_kind:     hidden_remainder_y
      - .offset:         158
        .size:           2
        .value_kind:     hidden_remainder_z
      - .offset:         176
        .size:           8
        .value_kind:     hidden_global_offset_x
      - .offset:         184
        .size:           8
        .value_kind:     hidden_global_offset_y
      - .offset:         192
        .size:           8
        .value_kind:     hidden_global_offset_z
      - .offset:         200
        .size:           2
        .value_kind:     hidden_grid_dims
      - .offset:         224
        .size:           8
        .value_kind:     hidden_multigrid_sync_arg
      - .offset:         256
        .size:           4
        .value_kind:     hidden_dynamic_lds_size
    .group_segment_fixed_size: 0
    .kernarg_segment_align: 8
    .kernarg_segment_size: 392
    .language:       OpenCL C
    .language_version:
      - 2
      - 0
    .max_flat_workgroup_size: 512
    .name:           _ZN2mk14fwd_megakernelILi0ELi16EEEvNS_4ArgsE
    .private_segment_fixed_size: 0
    .sgpr_count:     108
    .sgpr_spill_count: 0
    .symbol:         _ZN2mk14fwd_megakernelILi0ELi16EEEvNS_4ArgsE.kd
    .uniform_work_group_size: 1
    .uses_dynamic_stack: false
    .vgpr_count:     256
    .vgpr_spill_count: 0
    .wavefront_size: 64
